# mixer per-group RMSNorm row loops: 4 rows in flight, interleaved reductions
# baseline (speedup 1.0000x reference)
; #define LAS __attribute__((address_space(3)))
; __device__ __forceinline__ float bflo(unsigned u) { return __uint_as_float(u << 16); }
; __device__ __forceinline__ float bfhi(unsigned u) { return __uint_as_float(u & 0xffff0000u); }
; __device__ __forceinline__ void mixer_unit(LAS unsigned char* lds, int unit, const bf16* P, bf16* Y, const float* conv_w, const float* sgu_norm, const float* sgu_w, const float* sgu_b, int tid, int wave, int lane) {
;     ...
;         float w0[8], w1[8], w2[8];
;         { const f32x4 a0 = *(const __attribute__((address_space(1))) f32x4*)(conv_w + c8), a1 = *(const __attribute__((address_space(1))) f32x4*)(conv_w + c8 + 4), b0 = *(const __attribute__((address_space(1))) f32x4*)(conv_w + 256 + c8), b1 = *(const __attribute__((address_space(1))) f32x4*)(conv_w + 256 + c8 + 4), d0 = *(const __attribute__((address_space(1))) f32x4*)(conv_w + 512 + c8), d1 = *(const __attribute__((address_space(1))) f32x4*)(conv_w + 512 + c8 + 4);
; #pragma unroll
;           for (int e = 0; e < 4; ++e) { w0[e] = a0[e]; w0[4 + e] = a1[e]; w1[e] = b0[e]; w1[4 + e] = b1[e]; w2[e] = d0[e]; w2[4 + e] = d1[e]; } }
;         float pr_[6][8];
; #pragma unroll
;         for (int i = 0; i < 6; ++i) { const unsigned ga[4] = {gc[i].x, gc[i].y, gc[i].z, gc[i].w}, ha[4] = {hc[i].x, hc[i].y, hc[i].z, hc[i].w};
; #pragma unroll
;             for (int e = 0; e < 4; ++e) { pr_[i][2 * e] = bflo(ga[e]) * bflo(ha[e]); pr_[i][2 * e + 1] = bfhi(ga[e]) * bfhi(ha[e]); } }
; #pragma unroll
;         for (int i = 0; i < 4; ++i) { const unsigned ba[4] = {gb[i].x, gb[i].y, gb[i].z, gb[i].w}; float o[8];
; #pragma unroll
;             for (int e = 0; e < 4; ++e) { o[2 * e] = bflo(ba[e]) * (w0[2 * e] * pr_[i][2 * e] + w1[2 * e] * pr_[i + 1][2 * e] + w2[2 * e] * pr_[i + 2][2 * e]);
;                 o[2 * e + 1] = bfhi(ba[e]) * (w0[2 * e + 1] * pr_[i][2 * e + 1] + w1[2 * e + 1] * pr_[i + 1][2 * e + 1] + w2[2 * e + 1] * pr_[i + 2][2 * e + 1]); }
;             LAS f32x4* tp = (LAS f32x4*)(tile + (4 * rg + i) * 260 + c8); tp[0] = (f32x4){o[0], o[1], o[2], o[3]}; tp[1] = (f32x4){o[4], o[5], o[6], o[7]}; }
.LBB0_244:
	s_add_u32 s64, s89, s83
	s_addc_u32 s65, s33, 0
	v_lshlrev_b32_e32 v152, 2, v130
	global_load_dwordx4 v[128:131], v152, s[64:65] offset:16
	global_load_dwordx4 v[140:143], v152, s[64:65]
	global_load_dwordx4 v[132:135], v152, s[64:65] offset:1040
	global_load_dwordx4 v[144:147], v152, s[64:65] offset:1024
	global_load_dwordx4 v[136:139], v152, s[64:65] offset:2064
	global_load_dwordx4 v[148:151], v152, s[64:65] offset:2048
	s_add_i32 s33, 0, 0x11000
	v_add_u32_e32 v190, s33, v152
	s_waitcnt vmcnt(15)
	v_lshlrev_b32_e32 v152, 16, v108
	v_and_b32_e32 v153, 0xffff0000, v108
	s_waitcnt vmcnt(14)
	v_lshlrev_b32_e32 v154, 16, v112
	v_and_b32_e32 v155, 0xffff0000, v112
	v_lshlrev_b32_e32 v108, 16, v109
	v_and_b32_e32 v109, 0xffff0000, v109
	v_lshlrev_b32_e32 v112, 16, v113
	v_and_b32_e32 v113, 0xffff0000, v113
	v_pk_mul_f32 v[152:153], v[152:153], v[154:155]
	v_lshlrev_b32_e32 v154, 16, v104
	v_and_b32_e32 v155, 0xffff0000, v104
	v_lshlrev_b32_e32 v208, 16, v120
	v_and_b32_e32 v209, 0xffff0000, v120
	v_pk_mul_f32 v[112:113], v[108:109], v[112:113]
	v_lshlrev_b32_e32 v104, 16, v105
	v_and_b32_e32 v105, 0xffff0000, v105
	v_lshlrev_b32_e32 v108, 16, v121
	v_and_b32_e32 v109, 0xffff0000, v121
	v_pk_mul_f32 v[210:211], v[154:155], v[208:209]
	v_lshlrev_b32_e32 v154, 16, v124
	v_and_b32_e32 v155, 0xffff0000, v124
	v_lshlrev_b32_e32 v208, 16, v100
	v_and_b32_e32 v209, 0xffff0000, v100
	v_pk_mul_f32 v[108:109], v[104:105], v[108:109]
	v_lshlrev_b32_e32 v104, 16, v125
	v_and_b32_e32 v105, 0xffff0000, v125
	v_lshlrev_b32_e32 v100, 16, v101
	v_and_b32_e32 v101, 0xffff0000, v101
	v_pk_mul_f32 v[208:209], v[154:155], v[208:209]
	s_waitcnt vmcnt(13)
	v_lshlrev_b32_e32 v154, 16, v116
	v_and_b32_e32 v155, 0xffff0000, v116
	v_pk_mul_f32 v[100:101], v[104:105], v[100:101]
	v_lshlrev_b32_e32 v104, 16, v117
	v_and_b32_e32 v105, 0xffff0000, v117
	v_lshlrev_b32_e32 v120, 16, v102
	v_and_b32_e32 v121, 0xffff0000, v102
	v_lshlrev_b32_e32 v102, 16, v103
	v_and_b32_e32 v103, 0xffff0000, v103
	s_movk_i32 s33, 0x410
	s_movk_i32 s69, 0x410
	s_waitcnt vmcnt(2)
	v_pk_mul_f32 v[214:215], v[210:211], v[144:145]
	v_pk_mul_f32 v[116:117], v[108:109], v[146:147]
	v_pk_fma_f32 v[152:153], v[152:153], v[140:141], v[214:215]
	v_pk_fma_f32 v[112:113], v[112:113], v[142:143], v[116:117]
	s_waitcnt vmcnt(0)
	v_pk_fma_f32 v[152:153], v[208:209], v[148:149], v[152:153]
	v_pk_fma_f32 v[112:113], v[100:101], v[150:151], v[112:113]
	v_pk_mul_f32 v[152:153], v[152:153], v[154:155]
	v_pk_mul_f32 v[154:155], v[112:113], v[104:105]
	v_lshlrev_b32_e32 v104, 16, v110
	v_and_b32_e32 v105, 0xffff0000, v110
	v_lshlrev_b32_e32 v112, 16, v114
	v_and_b32_e32 v113, 0xffff0000, v114
	v_lshlrev_b32_e32 v110, 16, v111
	v_and_b32_e32 v111, 0xffff0000, v111
	v_lshlrev_b32_e32 v114, 16, v115
	v_and_b32_e32 v115, 0xffff0000, v115
	v_pk_mul_f32 v[116:117], v[104:105], v[112:113]
	v_lshlrev_b32_e32 v104, 16, v106
	v_and_b32_e32 v105, 0xffff0000, v106
	v_lshlrev_b32_e32 v112, 16, v122
	v_and_b32_e32 v113, 0xffff0000, v122
	v_pk_mul_f32 v[110:111], v[110:111], v[114:115]
	v_lshlrev_b32_e32 v106, 16, v107
	v_and_b32_e32 v107, 0xffff0000, v107
	v_lshlrev_b32_e32 v114, 16, v123
	v_and_b32_e32 v115, 0xffff0000, v123
	v_pk_mul_f32 v[112:113], v[104:105], v[112:113]
	v_lshlrev_b32_e32 v104, 16, v126
	v_and_b32_e32 v105, 0xffff0000, v126
	v_pk_mul_f32 v[114:115], v[106:107], v[114:115]
	v_lshlrev_b32_e32 v106, 16, v127
	v_and_b32_e32 v107, 0xffff0000, v127
	v_pk_mul_f32 v[104:105], v[104:105], v[120:121]
	v_lshlrev_b32_e32 v120, 16, v118
	v_and_b32_e32 v121, 0xffff0000, v118
	v_pk_mul_f32 v[124:125], v[112:113], v[132:133]
	v_pk_mul_f32 v[102:103], v[106:107], v[102:103]
	v_lshlrev_b32_e32 v106, 16, v119
	v_and_b32_e32 v107, 0xffff0000, v119
	v_pk_mul_f32 v[118:119], v[114:115], v[134:135]
	v_pk_fma_f32 v[116:117], v[116:117], v[128:129], v[124:125]
	v_pk_fma_f32 v[110:111], v[110:111], v[130:131], v[118:119]
	v_pk_fma_f32 v[116:117], v[104:105], v[136:137], v[116:117]
	v_pk_fma_f32 v[110:111], v[102:103], v[138:139], v[110:111]
	v_pk_mul_f32 v[116:117], v[116:117], v[120:121]
	v_pk_mul_f32 v[118:119], v[110:111], v[106:107]
	v_mad_u64_u32 v[110:111], s[64:65], v213, s33, v[190:191]
	ds_write_b128 v110, v[152:155]
	ds_write_b128 v110, v[116:119] offset:16
	v_lshlrev_b32_e32 v106, 16, v12
	v_and_b32_e32 v107, 0xffff0000, v12
	v_lshlrev_b32_e32 v116, 16, v88
	v_and_b32_e32 v117, 0xffff0000, v88
	v_lshlrev_b32_e32 v12, 16, v13
	v_and_b32_e32 v13, 0xffff0000, v13
	v_lshlrev_b32_e32 v88, 16, v89
	v_and_b32_e32 v89, 0xffff0000, v89
	v_pk_mul_f32 v[116:117], v[106:107], v[116:117]
	v_lshlrev_b32_e32 v106, 16, v96
	v_and_b32_e32 v107, 0xffff0000, v96
	v_pk_mul_f32 v[88:89], v[12:13], v[88:89]
	v_lshlrev_b32_e32 v12, 16, v97
	v_and_b32_e32 v13, 0xffff0000, v97
	v_pk_mul_f32 v[96:97], v[100:101], v[146:147]
	v_pk_mul_f32 v[118:119], v[208:209], v[144:145]
	v_pk_fma_f32 v[96:97], v[108:109], v[142:143], v[96:97]
	v_pk_fma_f32 v[118:119], v[210:211], v[140:141], v[118:119]
	v_pk_fma_f32 v[96:97], v[88:89], v[150:151], v[96:97]
	v_pk_fma_f32 v[118:119], v[116:117], v[148:149], v[118:119]
	v_pk_mul_f32 v[108:109], v[96:97], v[12:13]
	v_lshlrev_b32_e32 v12, 16, v14
	v_and_b32_e32 v13, 0xffff0000, v14
	v_lshlrev_b32_e32 v96, 16, v90
	v_and_b32_e32 v97, 0xffff0000, v90
	v_lshlrev_b32_e32 v14, 16, v15
	v_and_b32_e32 v15, 0xffff0000, v15
	v_lshlrev_b32_e32 v90, 16, v91
	v_and_b32_e32 v91, 0xffff0000, v91
	v_pk_mul_f32 v[106:107], v[118:119], v[106:107]
	v_pk_mul_f32 v[96:97], v[12:13], v[96:97]
	v_lshlrev_b32_e32 v12, 16, v98
	v_and_b32_e32 v13, 0xffff0000, v98
	v_pk_mul_f32 v[118:119], v[104:105], v[132:133]
; #define LAS __attribute__((address_space(3)))
; #define LDS_WAIT() asm volatile("s_waitcnt lgkmcnt(0)" ::: "memory")
; __device__ __forceinline__ float bflo(unsigned u) { return __uint_as_float(u << 16); }
; __device__ __forceinline__ float bfhi(unsigned u) { return __uint_as_float(u & 0xffff0000u); }
; __device__ __forceinline__ void mixer_unit(LAS unsigned char* lds, int unit, const bf16* P, bf16* Y, const float* conv_w, const float* sgu_norm, const float* sgu_w, const float* sgu_b, int tid, int wave, int lane) {
;     ...
;         for (int i = 0; i < 4; ++i) { const unsigned ba[4] = {gb[i].x, gb[i].y, gb[i].z, gb[i].w}; float o[8];
; #pragma unroll
;             for (int e = 0; e < 4; ++e) { o[2 * e] = bflo(ba[e]) * (w0[2 * e] * pr_[i][2 * e] + w1[2 * e] * pr_[i + 1][2 * e] + w2[2 * e] * pr_[i + 2][2 * e]);
;                 o[2 * e + 1] = bfhi(ba[e]) * (w0[2 * e + 1] * pr_[i][2 * e + 1] + w1[2 * e + 1] * pr_[i + 1][2 * e + 1] + w2[2 * e + 1] * pr_[i + 2][2 * e + 1]); }
;             LAS f32x4* tp = (LAS f32x4*)(tile + (4 * rg + i) * 260 + c8); tp[0] = (f32x4){o[0], o[1], o[2], o[3]}; tp[1] = (f32x4){o[4], o[5], o[6], o[7]}; }
;     }
;     LDS_WAIT(); __syncthreads();
;     norm_store_rows(tile, Y, t0, 0, wave, lane);
	v_pk_mul_f32 v[90:91], v[14:15], v[90:91]
	v_lshlrev_b32_e32 v14, 16, v99
	v_and_b32_e32 v15, 0xffff0000, v99
	v_pk_mul_f32 v[98:99], v[102:103], v[134:135]
	v_pk_fma_f32 v[112:113], v[112:113], v[128:129], v[118:119]
	v_pk_fma_f32 v[98:99], v[114:115], v[130:131], v[98:99]
	v_pk_fma_f32 v[112:113], v[96:97], v[136:137], v[112:113]
	v_pk_fma_f32 v[98:99], v[90:91], v[138:139], v[98:99]
	v_pk_mul_f32 v[12:13], v[112:113], v[12:13]
	v_pk_mul_f32 v[14:15], v[98:99], v[14:15]
	ds_write_b128 v110, v[106:109] offset:1040
	ds_write_b128 v110, v[12:15] offset:1056
	v_lshlrev_b32_e32 v12, 16, v20
	v_and_b32_e32 v13, 0xffff0000, v20
	v_lshlrev_b32_e32 v14, 16, v24
	v_and_b32_e32 v15, 0xffff0000, v24
	v_pk_mul_f32 v[98:99], v[12:13], v[14:15]
	v_pk_mul_f32 v[14:15], v[116:117], v[144:145]
	v_lshlrev_b32_e32 v12, 16, v92
	v_pk_fma_f32 v[14:15], v[208:209], v[140:141], v[14:15]
	v_and_b32_e32 v13, 0xffff0000, v92
	v_pk_fma_f32 v[14:15], v[98:99], v[148:149], v[14:15]
	v_lshlrev_b32_e32 v20, 16, v25
	v_pk_mul_f32 v[12:13], v[14:15], v[12:13]
	v_lshlrev_b32_e32 v14, 16, v21
	v_and_b32_e32 v15, 0xffff0000, v21
	v_and_b32_e32 v21, 0xffff0000, v25
	v_pk_mul_f32 v[24:25], v[14:15], v[20:21]
	v_pk_mul_f32 v[20:21], v[88:89], v[146:147]
	v_lshlrev_b32_e32 v14, 16, v93
	v_pk_fma_f32 v[20:21], v[100:101], v[142:143], v[20:21]
	v_and_b32_e32 v15, 0xffff0000, v93
	v_pk_fma_f32 v[20:21], v[24:25], v[150:151], v[20:21]
	v_lshlrev_b32_e32 v92, 16, v26
	v_pk_mul_f32 v[14:15], v[20:21], v[14:15]
	v_lshlrev_b32_e32 v20, 16, v22
	v_and_b32_e32 v21, 0xffff0000, v22
	v_and_b32_e32 v93, 0xffff0000, v26
	v_pk_mul_f32 v[100:101], v[96:97], v[132:133]
	v_lshlrev_b32_e32 v22, 16, v23
	v_and_b32_e32 v23, 0xffff0000, v23
	v_lshlrev_b32_e32 v26, 16, v27
	v_and_b32_e32 v27, 0xffff0000, v27
	v_pk_mul_f32 v[92:93], v[20:21], v[92:93]
	v_lshlrev_b32_e32 v20, 16, v94
	v_and_b32_e32 v21, 0xffff0000, v94
	v_pk_fma_f32 v[100:101], v[104:105], v[128:129], v[100:101]
	v_pk_mul_f32 v[26:27], v[22:23], v[26:27]
	v_lshlrev_b32_e32 v22, 16, v95
	v_and_b32_e32 v23, 0xffff0000, v95
	v_pk_mul_f32 v[94:95], v[90:91], v[134:135]
	v_pk_fma_f32 v[100:101], v[92:93], v[136:137], v[100:101]
	v_pk_fma_f32 v[94:95], v[102:103], v[130:131], v[94:95]
	v_pk_mul_f32 v[20:21], v[100:101], v[20:21]
	v_pk_fma_f32 v[94:95], v[26:27], v[138:139], v[94:95]
	s_nop 0
	v_pk_mul_f32 v[22:23], v[94:95], v[22:23]
	ds_write_b128 v110, v[12:15] offset:2080
	ds_write_b128 v110, v[20:23] offset:2096
	v_lshlrev_b32_e32 v12, 16, v8
	v_and_b32_e32 v13, 0xffff0000, v8
	v_lshlrev_b32_e32 v14, 16, v16
	v_and_b32_e32 v15, 0xffff0000, v16
	v_pk_mul_f32 v[20:21], v[98:99], v[144:145]
	v_pk_mul_f32 v[12:13], v[12:13], v[14:15]
	v_pk_fma_f32 v[20:21], v[116:117], v[140:141], v[20:21]
	v_lshlrev_b32_e32 v14, 16, v28
	v_and_b32_e32 v15, 0xffff0000, v28
	v_pk_fma_f32 v[12:13], v[12:13], v[148:149], v[20:21]
	v_lshlrev_b32_e32 v8, 16, v9
	v_pk_mul_f32 v[12:13], v[12:13], v[14:15]
	v_and_b32_e32 v9, 0xffff0000, v9
	v_lshlrev_b32_e32 v14, 16, v17
	v_and_b32_e32 v15, 0xffff0000, v17
	v_pk_mul_f32 v[16:17], v[24:25], v[146:147]
	v_pk_mul_f32 v[8:9], v[8:9], v[14:15]
	v_pk_fma_f32 v[16:17], v[88:89], v[142:143], v[16:17]
	v_lshlrev_b32_e32 v14, 16, v29
	v_and_b32_e32 v15, 0xffff0000, v29
	v_pk_fma_f32 v[8:9], v[8:9], v[150:151], v[16:17]
	v_lshlrev_b32_e32 v16, 16, v18
	v_pk_mul_f32 v[14:15], v[8:9], v[14:15]
	v_lshlrev_b32_e32 v8, 16, v10
	v_and_b32_e32 v9, 0xffff0000, v10
	v_and_b32_e32 v17, 0xffff0000, v18
	v_pk_mul_f32 v[20:21], v[92:93], v[132:133]
	v_pk_mul_f32 v[8:9], v[8:9], v[16:17]
	v_pk_fma_f32 v[20:21], v[96:97], v[128:129], v[20:21]
	v_lshlrev_b32_e32 v16, 16, v30
	v_and_b32_e32 v17, 0xffff0000, v30
	v_pk_fma_f32 v[8:9], v[8:9], v[136:137], v[20:21]
	v_lshlrev_b32_e32 v10, 16, v11
	v_pk_mul_f32 v[8:9], v[8:9], v[16:17]
	v_and_b32_e32 v11, 0xffff0000, v11
	v_lshlrev_b32_e32 v16, 16, v19
	v_and_b32_e32 v17, 0xffff0000, v19
	v_pk_mul_f32 v[18:19], v[26:27], v[134:135]
	v_pk_mul_f32 v[10:11], v[10:11], v[16:17]
	v_pk_fma_f32 v[18:19], v[90:91], v[130:131], v[18:19]
	v_lshlrev_b32_e32 v16, 16, v31
	v_and_b32_e32 v17, 0xffff0000, v31
	v_pk_fma_f32 v[10:11], v[10:11], v[138:139], v[18:19]
	s_nop 0
	v_pk_mul_f32 v[10:11], v[10:11], v[16:17]
	v_or_b32_e32 v16, 3, v212
	v_mad_u64_u32 v[16:17], s[64:65], v16, s33, v[190:191]
	ds_write_b128 v16, v[12:15]
	ds_write_b128 v16, v[8:11] offset:16
	s_waitcnt lgkmcnt(0)
	v_readlane_b32 s33, v253, 63
	v_lshl_add_u64 v[8:9], v[156:157], 1, s[84:85]
	s_waitcnt lgkmcnt(0)
	v_lshl_add_u32 v104, v225, 4, s33
	s_mov_b32 s33, 0
	v_mov_b32_e32 v10, v104
	s_barrier
	v_add_u32_e32 v11, 0xfffffbf0, v10
; #define LAS __attribute__((address_space(3)))
; __device__ __forceinline__ unsigned pk2(float lo, float hi) { return pg8::cvt_pk_bf16(lo, hi); }
; __device__ __forceinline__ void norm_store_rows(const LAS float* tile, bf16* Y, int t0, int coff, int wave, int lane) {
; #pragma unroll 2
;     for (int i = 0; i < 8; ++i) { const int r = wave * 8 + i; const f32x4 v = *(const LAS f32x4*)(tile + r * 260 + lane * 4);
;         const float ss = wave_sum((v[0] * v[0] + v[1] * v[1]) + (v[2] * v[2] + v[3] * v[3]));
;         const float rs = __builtin_amdgcn_rsqf(ss * (1.0f / 256.0f) + EPS);
;         v2u o; o.x = pk2(v[0] * rs, v[1] * rs); o.y = pk2(v[2] * rs, v[3] * rs);
;         *(__attribute__((address_space(1))) v2u*)(Y + (size_t)(t0 + r) * DM + coff + lane * 4) = o; }
; }
.LBB0_245:
	ds_read_b128 v[12:15], v11
	ds_read_b128 v[16:19], v11 offset:1040
	ds_read_b128 v[148:151], v11 offset:2080
	ds_read_b128 v[152:155], v11 offset:3120
	s_add_i32 s64, s95, s33
	s_ashr_i32 s65, s64, 31
	s_lshl_b64 s[66:67], s[64:65], 11
	v_add_u32_e32 v11, 0x1040, v11
	v_lshl_add_u64 v[248:249], v[8:9], 0, s[66:67]
	s_waitcnt lgkmcnt(3)
	v_pk_mul_f32 v[20:21], v[12:13], v[12:13]
	v_mul_f32_e32 v10, v14, v14
	s_waitcnt lgkmcnt(2)
	v_pk_mul_f32 v[240:241], v[16:17], v[16:17]
	v_mul_f32_e32 v250, v18, v18
	s_waitcnt lgkmcnt(1)
	v_pk_mul_f32 v[242:243], v[148:149], v[148:149]
	v_mul_f32_e32 v251, v150, v150
	s_waitcnt lgkmcnt(0)
	v_pk_mul_f32 v[244:245], v[152:153], v[152:153]
	v_mul_f32_e32 v246, v154, v154
	v_add_f32_e32 v20, v21, v20
	v_add_f32_e32 v240, v241, v240
	v_add_f32_e32 v242, v243, v242
	v_add_f32_e32 v244, v245, v244
	v_mul_f32_e32 v21, v15, v15
	v_mul_f32_e32 v241, v19, v19
	v_mul_f32_e32 v243, v151, v151
	v_mul_f32_e32 v245, v155, v155
	v_add_f32_e32 v10, v10, v21
	v_add_f32_e32 v250, v250, v241
	v_add_f32_e32 v251, v251, v243
	v_add_f32_e32 v246, v246, v245
	v_add_f32_e32 v20, v20, v10
	v_add_f32_e32 v240, v240, v250
	v_add_f32_e32 v242, v242, v251
	v_add_f32_e32 v244, v244, v246
	v_add_f32_dpp v20, v20, v20 quad_perm:[1,0,3,2] row_mask:0xf bank_mask:0xf bound_ctrl:1
	v_add_f32_dpp v240, v240, v240 quad_perm:[1,0,3,2] row_mask:0xf bank_mask:0xf bound_ctrl:1
	v_add_f32_dpp v242, v242, v242 quad_perm:[1,0,3,2] row_mask:0xf bank_mask:0xf bound_ctrl:1
	v_add_f32_dpp v244, v244, v244 quad_perm:[1,0,3,2] row_mask:0xf bank_mask:0xf bound_ctrl:1
	v_add_f32_dpp v20, v20, v20 quad_perm:[2,3,0,1] row_mask:0xf bank_mask:0xf bound_ctrl:1
	v_add_f32_dpp v240, v240, v240 quad_perm:[2,3,0,1] row_mask:0xf bank_mask:0xf bound_ctrl:1
	v_add_f32_dpp v242, v242, v242 quad_perm:[2,3,0,1] row_mask:0xf bank_mask:0xf bound_ctrl:1
	v_add_f32_dpp v244, v244, v244 quad_perm:[2,3,0,1] row_mask:0xf bank_mask:0xf bound_ctrl:1
	v_add_f32_dpp v20, v20, v20 row_half_mirror row_mask:0xf bank_mask:0xf bound_ctrl:1
	v_add_f32_dpp v240, v240, v240 row_half_mirror row_mask:0xf bank_mask:0xf bound_ctrl:1
	v_add_f32_dpp v242, v242, v242 row_half_mirror row_mask:0xf bank_mask:0xf bound_ctrl:1
	v_add_f32_dpp v244, v244, v244 row_half_mirror row_mask:0xf bank_mask:0xf bound_ctrl:1
	v_add_f32_dpp v20, v20, v20 row_mirror row_mask:0xf bank_mask:0xf bound_ctrl:1
	v_add_f32_dpp v240, v240, v240 row_mirror row_mask:0xf bank_mask:0xf bound_ctrl:1
	v_add_f32_dpp v242, v242, v242 row_mirror row_mask:0xf bank_mask:0xf bound_ctrl:1
	v_add_f32_dpp v244, v244, v244 row_mirror row_mask:0xf bank_mask:0xf bound_ctrl:1
	v_readlane_b32 s66, v20, 16
	v_readlane_b32 s67, v20, 48
	v_readlane_b32 s64, v20, 0
	v_readlane_b32 s65, v20, 32
	v_mov_b32_e32 v20, s66
	v_mov_b32_e32 v21, s67
	v_pk_add_f32 v[20:21], s[64:65], v[20:21]
	s_nop 0
	v_add_f32_e32 v20, v20, v21
	v_fmamk_f32 v20, v20, 0x3b800000, v220
	v_rsq_f32_e32 v20, v20
	v_readlane_b32 s66, v240, 16
	v_readlane_b32 s67, v240, 48
	v_readlane_b32 s64, v240, 0
	v_readlane_b32 s65, v240, 32
	v_mov_b32_e32 v240, s66
	v_mov_b32_e32 v241, s67
	v_pk_add_f32 v[240:241], s[64:65], v[240:241]
	s_nop 0
	v_add_f32_e32 v240, v240, v241
	v_fmamk_f32 v240, v240, 0x3b800000, v220
	v_rsq_f32_e32 v240, v240
	v_readlane_b32 s66, v242, 16
	v_readlane_b32 s67, v242, 48
	v_readlane_b32 s64, v242, 0
	v_readlane_b32 s65, v242, 32
	v_mov_b32_e32 v242, s66
	v_mov_b32_e32 v243, s67
	v_pk_add_f32 v[242:243], s[64:65], v[242:243]
	s_nop 0
	v_add_f32_e32 v242, v242, v243
	v_fmamk_f32 v242, v242, 0x3b800000, v220
	v_rsq_f32_e32 v242, v242
	v_readlane_b32 s66, v244, 16
	v_readlane_b32 s67, v244, 48
	v_readlane_b32 s64, v244, 0
	v_readlane_b32 s65, v244, 32
	v_mov_b32_e32 v244, s66
	v_mov_b32_e32 v245, s67
	v_pk_add_f32 v[244:245], s[64:65], v[244:245]
	s_nop 0
	v_add_f32_e32 v244, v244, v245
	v_fmamk_f32 v244, v244, 0x3b800000, v220
	v_rsq_f32_e32 v244, v244
	s_nop 0
	v_mul_f32_e32 v12, v12, v20
	v_mul_f32_e32 v13, v13, v20
	v_cvt_pk_bf16_f32 v12, v12, v13
	v_mul_f32_e32 v13, v14, v20
	v_mul_f32_e32 v10, v15, v20
	v_cvt_pk_bf16_f32 v13, v13, v10
	v_mul_f32_e32 v16, v16, v240
	v_mul_f32_e32 v17, v17, v240
	v_cvt_pk_bf16_f32 v16, v16, v17
	v_mul_f32_e32 v17, v18, v240
	v_mul_f32_e32 v250, v19, v240
	v_cvt_pk_bf16_f32 v17, v17, v250
	v_mul_f32_e32 v148, v148, v242
	v_mul_f32_e32 v149, v149, v242
	v_cvt_pk_bf16_f32 v148, v148, v149
	v_mul_f32_e32 v149, v150, v242
	v_mul_f32_e32 v251, v151, v242
	v_cvt_pk_bf16_f32 v149, v149, v251
	v_mul_f32_e32 v152, v152, v244
	v_mul_f32_e32 v153, v153, v244
	v_cvt_pk_bf16_f32 v152, v152, v153
	v_mul_f32_e32 v153, v154, v244
	v_mul_f32_e32 v246, v155, v244
	v_cvt_pk_bf16_f32 v153, v153, v246
	global_store_dwordx2 v[248:249], v[12:13], off
	global_store_dwordx2 v[248:249], v[16:17], off offset:2048
	s_add_i32 s64, s95, s33
	s_add_i32 s64, s64, 2
	s_ashr_i32 s65, s64, 31
	s_lshl_b64 s[66:67], s[64:65], 11
	s_add_i32 s33, s33, 4
	v_lshl_add_u64 v[248:249], v[8:9], 0, s[66:67]
	global_store_dwordx2 v[248:249], v[148:149], off
	global_store_dwordx2 v[248:249], v[152:153], off offset:2048
	s_cmp_lg_u32 s33, 8
	s_cbranch_scc1 .LBB0_245
	v_readlane_b32 s33, v255, 12
	s_add_u32 s64, s25, s33
	s_addc_u32 s65, s88, 0
	v_lshl_add_u64 v[8:9], v[156:157], 2, s[64:65]
	global_load_dwordx4 v[8:11], v[8:9], off
	s_movk_i32 s25, 0x440
	v_mul_lo_u32 v13, v225, s25
	v_and_b32_e32 v12, 56, v156
	s_andn2_b64 vcc, exec, s[62:63]
	v_add_u32_e32 v13, 0, v13
	s_cbranch_vccz .LBB0_279
	s_andn2_b64 vcc, exec, s[60:61]
	s_cbranch_vccz .LBB0_280

; #define LDS_WAIT() asm volatile("s_waitcnt lgkmcnt(0)" ::: "memory")
; __device__ __forceinline__ void mixer_unit(LAS unsigned char* lds, int unit, const bf16* P, bf16* Y, const float* conv_w, const float* sgu_norm, const float* sgu_w, const float* sgu_b, int tid, int wave, int lane) {
;     ...
; #pragma unroll
;         for (int j = 0; j < 16; ++j) { const int rl = 32 * rh + (j & 3) + 8 * (j >> 2) + 4 * hi;
;             tile[rl * 260 + h * 64 + r32] = ug0[j] * (o0[j] + bbv[j]);
;             tile[rl * 260 + h * 64 + 32 + r32] = ug1[j] * (o1[j] + bbv[j]); }
;     }
;     LDS_WAIT(); __syncthreads();
;     norm_store_rows(tile, Y, t0, 256, wave, lane);
.LBB0_276:
	s_waitcnt vmcnt(35)
	v_lshlrev_b32_e32 v32, 16, v106
	s_waitcnt vmcnt(25)
	s_nop 3
	v_add_f32_e32 v0, v92, v0
	v_lshlrev_b32_e32 v33, 16, v107
	v_mul_f32_e32 v0, v0, v32
	v_mul_lo_u32 v32, v105, s69
	v_lshlrev_b32_e32 v64, 2, v224
	v_readlane_b32 s0, v252, 14
	v_add_f32_e32 v16, v92, v16
	v_mul_f32_e32 v16, v16, v33
	v_add3_u32 v32, s0, v32, v64
	v_lshlrev_b32_e32 v34, 16, v108
	v_lshlrev_b32_e32 v35, 16, v109
	ds_write2_b32 v32, v0, v16 offset1:32
	v_add_f32_e32 v0, v93, v1
	v_add_f32_e32 v1, v93, v17
	v_mul_f32_e32 v0, v0, v34
	v_mul_f32_e32 v1, v1, v35
	v_add_u32_e32 v16, 0x400, v32
	v_lshlrev_b32_e32 v36, 16, v110
	v_lshlrev_b32_e32 v37, 16, v111
	ds_write2_b32 v16, v0, v1 offset0:4 offset1:36
	v_add_f32_e32 v0, v94, v2
	v_add_f32_e32 v1, v94, v18
	v_mul_f32_e32 v0, v0, v36
	v_mul_f32_e32 v1, v1, v37
	v_add_u32_e32 v2, 0x800, v32
	v_lshlrev_b32_e32 v38, 16, v112
	v_lshlrev_b32_e32 v39, 16, v113
	ds_write2_b32 v2, v0, v1 offset0:8 offset1:40
	v_add_f32_e32 v0, v95, v3
	v_add_f32_e32 v1, v95, v19
	v_mul_f32_e32 v0, v0, v38
	v_mul_f32_e32 v1, v1, v39
	v_add_u32_e32 v2, 0xc00, v32
	v_lshlrev_b32_e32 v40, 16, v114
	v_lshlrev_b32_e32 v41, 16, v115
	ds_write2_b32 v2, v0, v1 offset0:12 offset1:44
	s_waitcnt vmcnt(24)
	v_add_f32_e32 v0, v88, v4
	v_add_f32_e32 v1, v88, v20
	v_mul_f32_e32 v0, v0, v40
	v_mul_f32_e32 v1, v1, v41
	v_add_u32_e32 v2, 0x2000, v32
	s_waitcnt vmcnt(23)
	v_lshlrev_b32_e32 v42, 16, v116
	s_waitcnt vmcnt(22)
	v_lshlrev_b32_e32 v43, 16, v117
	ds_write2_b32 v2, v0, v1 offset0:32 offset1:64
	v_add_f32_e32 v0, v89, v5
	v_add_f32_e32 v1, v89, v21
	v_mul_f32_e32 v0, v0, v42
	v_mul_f32_e32 v1, v1, v43
	v_add_u32_e32 v2, 0x2400, v32
	s_waitcnt vmcnt(21)
	v_lshlrev_b32_e32 v44, 16, v118
	s_waitcnt vmcnt(20)
	v_lshlrev_b32_e32 v45, 16, v119
	ds_write2_b32 v2, v0, v1 offset0:36 offset1:68
	v_add_f32_e32 v0, v90, v6
	v_add_f32_e32 v1, v90, v22
	v_mul_f32_e32 v0, v0, v44
	v_mul_f32_e32 v1, v1, v45
	v_add_u32_e32 v2, 0x2800, v32
	s_waitcnt vmcnt(19)
	v_lshlrev_b32_e32 v46, 16, v120
	s_waitcnt vmcnt(18)
	v_lshlrev_b32_e32 v47, 16, v121
	ds_write2_b32 v2, v0, v1 offset0:40 offset1:72
	v_add_f32_e32 v0, v91, v7
	v_add_f32_e32 v1, v91, v23
	v_mul_f32_e32 v0, v0, v46
	v_mul_f32_e32 v1, v1, v47
	v_add_u32_e32 v2, 0x2c00, v32
	s_waitcnt vmcnt(17)
	v_lshlrev_b32_e32 v48, 16, v122
	s_waitcnt vmcnt(16)
	v_lshlrev_b32_e32 v49, 16, v123
	ds_write2_b32 v2, v0, v1 offset0:44 offset1:76
	s_waitcnt vmcnt(7)
	v_add_f32_e32 v0, v100, v8
	v_add_f32_e32 v1, v100, v24
	v_mul_f32_e32 v0, v0, v48
	v_mul_f32_e32 v1, v1, v49
	v_add_u32_e32 v2, 0x4000, v32
	v_lshlrev_b32_e32 v50, 16, v124
	v_lshlrev_b32_e32 v51, 16, v125
	ds_write2_b32 v2, v0, v1 offset0:64 offset1:96
	v_add_f32_e32 v0, v101, v9
	v_add_f32_e32 v1, v101, v25
	v_mul_f32_e32 v0, v0, v50
	v_mul_f32_e32 v1, v1, v51
	v_add_u32_e32 v2, 0x4400, v32
	v_lshlrev_b32_e32 v52, 16, v126
	v_lshlrev_b32_e32 v53, 16, v127
	ds_write2_b32 v2, v0, v1 offset0:68 offset1:100
	v_add_f32_e32 v0, v102, v10
	v_add_f32_e32 v1, v102, v26
	v_mul_f32_e32 v0, v0, v52
	v_mul_f32_e32 v1, v1, v53
	v_add_u32_e32 v2, 0x4800, v32
	v_lshlrev_b32_e32 v54, 16, v128
	v_lshlrev_b32_e32 v55, 16, v129
	ds_write2_b32 v2, v0, v1 offset0:72 offset1:104
	v_add_f32_e32 v0, v103, v11
	v_add_f32_e32 v1, v103, v27
	v_mul_f32_e32 v0, v0, v54
	v_mul_f32_e32 v1, v1, v55
	v_add_u32_e32 v2, 0x4c00, v32
	v_lshlrev_b32_e32 v56, 16, v130
	v_lshlrev_b32_e32 v57, 16, v131
	ds_write2_b32 v2, v0, v1 offset0:76 offset1:108
	s_waitcnt vmcnt(6)
	v_add_f32_e32 v0, v96, v12
	v_add_f32_e32 v1, v96, v28
	v_mul_f32_e32 v0, v0, v56
	v_mul_f32_e32 v1, v1, v57
	v_add_u32_e32 v2, 0x6000, v32
	s_waitcnt vmcnt(5)
	v_lshlrev_b32_e32 v58, 16, v132
	s_waitcnt vmcnt(4)
	v_lshlrev_b32_e32 v59, 16, v133
	ds_write2_b32 v2, v0, v1 offset0:96 offset1:128
	v_add_f32_e32 v0, v97, v13
	v_add_f32_e32 v1, v97, v29
	v_mul_f32_e32 v0, v0, v58
	v_mul_f32_e32 v1, v1, v59
	v_add_u32_e32 v2, 0x6400, v32
	s_waitcnt vmcnt(3)
	v_lshlrev_b32_e32 v60, 16, v134
	s_waitcnt vmcnt(2)
	v_lshlrev_b32_e32 v61, 16, v135
	ds_write2_b32 v2, v0, v1 offset0:100 offset1:132
	v_add_f32_e32 v0, v98, v14
	v_add_f32_e32 v1, v98, v30
	v_mul_f32_e32 v0, v0, v60
	v_mul_f32_e32 v1, v1, v61
	v_add_u32_e32 v2, 0x6800, v32
	s_waitcnt vmcnt(1)
	v_lshlrev_b32_e32 v62, 16, v136
	s_waitcnt vmcnt(0)
	v_lshlrev_b32_e32 v63, 16, v137
	ds_write2_b32 v2, v0, v1 offset0:104 offset1:136
	v_add_f32_e32 v0, v99, v15
	v_add_f32_e32 v1, v99, v31
	v_mul_f32_e32 v0, v0, v62
	v_mul_f32_e32 v1, v1, v63
	v_add_u32_e32 v2, 0x6c00, v32
	ds_write2_b32 v2, v0, v1 offset0:108 offset1:140
	s_waitcnt lgkmcnt(0)
	v_lshl_add_u64 v[0:1], v[156:157], 1, s[86:87]
	s_mov_b32 s0, 0
	s_waitcnt lgkmcnt(0)
	s_barrier
	v_add_u32_e32 v2, 0xfffffbf0, v104
; #define LAS __attribute__((address_space(3)))
; #define LDS_WAIT() asm volatile("s_waitcnt lgkmcnt(0)" ::: "memory")
; __device__ __forceinline__ unsigned pk2(float lo, float hi) { return pg8::cvt_pk_bf16(lo, hi); }
; __device__ __forceinline__ void norm_store_rows(const LAS float* tile, bf16* Y, int t0, int coff, int wave, int lane) {
; #pragma unroll 2
;     for (int i = 0; i < 8; ++i) { const int r = wave * 8 + i; const f32x4 v = *(const LAS f32x4*)(tile + r * 260 + lane * 4);
;         const float ss = wave_sum((v[0] * v[0] + v[1] * v[1]) + (v[2] * v[2] + v[3] * v[3]));
;         const float rs = __builtin_amdgcn_rsqf(ss * (1.0f / 256.0f) + EPS);
;         v2u o; o.x = pk2(v[0] * rs, v[1] * rs); o.y = pk2(v[2] * rs, v[3] * rs);
;         *(__attribute__((address_space(1))) v2u*)(Y + (size_t)(t0 + r) * DM + coff + lane * 4) = o; }
; }
; __device__ __forceinline__ void mixer_unit(LAS unsigned char* lds, int unit, const bf16* P, bf16* Y, const float* conv_w, const float* sgu_norm, const float* sgu_w, const float* sgu_b, int tid, int wave, int lane) {
;     ...
;     norm_store_rows(tile, Y, t0, 256, wave, lane);
;     LDS_WAIT(); __syncthreads();
.LBB0_277:
	ds_read_b128 v[4:7], v2
	ds_read_b128 v[8:11], v2 offset:1040
	ds_read_b128 v[12:15], v2 offset:2080
	ds_read_b128 v[16:19], v2 offset:3120
	s_add_i32 s6, s95, s0
	s_ashr_i32 s7, s6, 31
	s_lshl_b64 s[8:9], s[6:7], 11
	v_add_u32_e32 v2, 0x1040, v2
	v_lshl_add_u64 v[32:33], v[0:1], 0, s[8:9]
	s_waitcnt lgkmcnt(3)
	v_pk_mul_f32 v[20:21], v[4:5], v[4:5]
	v_mul_f32_e32 v28, v6, v6
	s_waitcnt lgkmcnt(2)
	v_pk_mul_f32 v[22:23], v[8:9], v[8:9]
	v_mul_f32_e32 v29, v10, v10
	s_waitcnt lgkmcnt(1)
	v_pk_mul_f32 v[24:25], v[12:13], v[12:13]
	v_mul_f32_e32 v30, v14, v14
	s_waitcnt lgkmcnt(0)
	v_pk_mul_f32 v[26:27], v[16:17], v[16:17]
	v_mul_f32_e32 v31, v18, v18
	v_add_f32_e32 v20, v21, v20
	v_add_f32_e32 v22, v23, v22
	v_add_f32_e32 v24, v25, v24
	v_add_f32_e32 v26, v27, v26
	v_mul_f32_e32 v21, v7, v7
	v_mul_f32_e32 v23, v11, v11
	v_mul_f32_e32 v25, v15, v15
	v_mul_f32_e32 v27, v19, v19
	v_add_f32_e32 v28, v28, v21
	v_add_f32_e32 v29, v29, v23
	v_add_f32_e32 v30, v30, v25
	v_add_f32_e32 v31, v31, v27
	v_add_f32_e32 v20, v20, v28
	v_add_f32_e32 v22, v22, v29
	v_add_f32_e32 v24, v24, v30
	v_add_f32_e32 v26, v26, v31
	v_add_f32_dpp v20, v20, v20 quad_perm:[1,0,3,2] row_mask:0xf bank_mask:0xf bound_ctrl:1
	v_add_f32_dpp v22, v22, v22 quad_perm:[1,0,3,2] row_mask:0xf bank_mask:0xf bound_ctrl:1
	v_add_f32_dpp v24, v24, v24 quad_perm:[1,0,3,2] row_mask:0xf bank_mask:0xf bound_ctrl:1
	v_add_f32_dpp v26, v26, v26 quad_perm:[1,0,3,2] row_mask:0xf bank_mask:0xf bound_ctrl:1
	v_add_f32_dpp v20, v20, v20 quad_perm:[2,3,0,1] row_mask:0xf bank_mask:0xf bound_ctrl:1
	v_add_f32_dpp v22, v22, v22 quad_perm:[2,3,0,1] row_mask:0xf bank_mask:0xf bound_ctrl:1
	v_add_f32_dpp v24, v24, v24 quad_perm:[2,3,0,1] row_mask:0xf bank_mask:0xf bound_ctrl:1
	v_add_f32_dpp v26, v26, v26 quad_perm:[2,3,0,1] row_mask:0xf bank_mask:0xf bound_ctrl:1
	v_add_f32_dpp v20, v20, v20 row_half_mirror row_mask:0xf bank_mask:0xf bound_ctrl:1
	v_add_f32_dpp v22, v22, v22 row_half_mirror row_mask:0xf bank_mask:0xf bound_ctrl:1
	v_add_f32_dpp v24, v24, v24 row_half_mirror row_mask:0xf bank_mask:0xf bound_ctrl:1
	v_add_f32_dpp v26, v26, v26 row_half_mirror row_mask:0xf bank_mask:0xf bound_ctrl:1
	v_add_f32_dpp v20, v20, v20 row_mirror row_mask:0xf bank_mask:0xf bound_ctrl:1
	v_add_f32_dpp v22, v22, v22 row_mirror row_mask:0xf bank_mask:0xf bound_ctrl:1
	v_add_f32_dpp v24, v24, v24 row_mirror row_mask:0xf bank_mask:0xf bound_ctrl:1
	v_add_f32_dpp v26, v26, v26 row_mirror row_mask:0xf bank_mask:0xf bound_ctrl:1
	v_readlane_b32 s1, v20, 16
	v_readlane_b32 s5, v20, 48
	v_readlane_b32 s8, v20, 0
	v_readlane_b32 s9, v20, 32
	v_mov_b32_e32 v20, s1
	v_mov_b32_e32 v21, s5
	v_pk_add_f32 v[20:21], s[8:9], v[20:21]
	s_nop 0
	v_add_f32_e32 v20, v20, v21
	v_fmamk_f32 v20, v20, 0x3b800000, v220
	v_rsq_f32_e32 v20, v20
	v_readlane_b32 s1, v22, 16
	v_readlane_b32 s5, v22, 48
	v_readlane_b32 s8, v22, 0
	v_readlane_b32 s9, v22, 32
	v_mov_b32_e32 v22, s1
	v_mov_b32_e32 v23, s5
	v_pk_add_f32 v[22:23], s[8:9], v[22:23]
	s_nop 0
	v_add_f32_e32 v22, v22, v23
	v_fmamk_f32 v22, v22, 0x3b800000, v220
	v_rsq_f32_e32 v22, v22
	v_readlane_b32 s1, v24, 16
	v_readlane_b32 s5, v24, 48
	v_readlane_b32 s8, v24, 0
	v_readlane_b32 s9, v24, 32
	v_mov_b32_e32 v24, s1
	v_mov_b32_e32 v25, s5
	v_pk_add_f32 v[24:25], s[8:9], v[24:25]
	s_nop 0
	v_add_f32_e32 v24, v24, v25
	v_fmamk_f32 v24, v24, 0x3b800000, v220
	v_rsq_f32_e32 v24, v24
	v_readlane_b32 s1, v26, 16
	v_readlane_b32 s5, v26, 48
	v_readlane_b32 s8, v26, 0
	v_readlane_b32 s9, v26, 32
	v_mov_b32_e32 v26, s1
	v_mov_b32_e32 v27, s5
	v_pk_add_f32 v[26:27], s[8:9], v[26:27]
	s_nop 0
	v_add_f32_e32 v26, v26, v27
	v_fmamk_f32 v26, v26, 0x3b800000, v220
	v_rsq_f32_e32 v26, v26
	s_nop 0
	v_mul_f32_e32 v4, v4, v20
	v_mul_f32_e32 v5, v5, v20
	v_cvt_pk_bf16_f32 v4, v4, v5
	v_mul_f32_e32 v5, v6, v20
	v_mul_f32_e32 v28, v7, v20
	v_cvt_pk_bf16_f32 v5, v5, v28
	v_mul_f32_e32 v8, v8, v22
	v_mul_f32_e32 v9, v9, v22
	v_cvt_pk_bf16_f32 v8, v8, v9
	v_mul_f32_e32 v9, v10, v22
	v_mul_f32_e32 v29, v11, v22
	v_cvt_pk_bf16_f32 v9, v9, v29
	v_mul_f32_e32 v12, v12, v24
	v_mul_f32_e32 v13, v13, v24
	v_cvt_pk_bf16_f32 v12, v12, v13
	v_mul_f32_e32 v13, v14, v24
	v_mul_f32_e32 v30, v15, v24
	v_cvt_pk_bf16_f32 v13, v13, v30
	v_mul_f32_e32 v16, v16, v26
	v_mul_f32_e32 v17, v17, v26
	v_cvt_pk_bf16_f32 v16, v16, v17
	v_mul_f32_e32 v17, v18, v26
	v_mul_f32_e32 v31, v19, v26
	v_cvt_pk_bf16_f32 v17, v17, v31
	global_store_dwordx2 v[32:33], v[4:5], off
	global_store_dwordx2 v[32:33], v[8:9], off offset:2048
	s_add_i32 s6, s95, s0
	s_add_i32 s6, s6, 2
	s_ashr_i32 s7, s6, 31
	s_lshl_b64 s[8:9], s[6:7], 11
	s_add_i32 s0, s0, 4
	v_lshl_add_u64 v[32:33], v[0:1], 0, s[8:9]
	global_store_dwordx2 v[32:33], v[12:13], off
	global_store_dwordx2 v[32:33], v[16:17], off offset:2048
	s_cmp_lg_u32 s0, 8
	s_cbranch_scc1 .LBB0_277
	s_waitcnt lgkmcnt(0)
	v_readlane_b32 s0, v254, 0
	s_add_i32 s2, s2, s96
	s_add_i32 s95, s95, s0
	s_cmpk_gt_i32 s2, 0xff
	s_barrier
	s_cbranch_scc0 .LBB0_157
	s_branch .LBB0_293
